# P7 fused epilogue: the 16 residual-base loads hoisted ahead of the row loop (same as P5), on top of v014
# speedup vs baseline: 1.0034x; 1.0034x over previous
.LBB0_856:
	s_lshl_b32 s3, s13, 8
	s_lshl_b32 s0, s2, 5
	s_lshl_b32 s1, s12, 8
	v_add_u32_e32 v132, s3, v172
	s_or_b32 s0, s1, s0
	v_ashrrev_i32_e32 v133, 31, v132
	v_and_or_b32 v130, v150, 24, s0
	v_lshlrev_b64 v[134:135], 12, v[132:133]
	v_ashrrev_i32_e32 v131, 31, v130
	v_lshl_add_u64 v[134:135], s[10:11], 0, v[134:135]
	v_lshl_add_u64 v[138:139], v[130:131], 1, v[134:135]
	s_barrier
	v_lshlrev_b32_e32 v250, 12, v132
	v_lshl_add_u32 v250, v130, 1, v250
	global_load_dwordx4 v[186:189], v250, s[10:11] nt
	global_load_dwordx4 v[190:193], v250, s[10:11] offset:256 nt
	s_add_u32 s14, s10, 0x10000
	s_addc_u32 s15, s11, 0
	global_load_dwordx4 v[194:197], v250, s[14:15] nt
	global_load_dwordx4 v[198:201], v250, s[14:15] offset:256 nt
	s_add_u32 s14, s10, 0x20000
	s_addc_u32 s15, s11, 0
	global_load_dwordx4 v[202:205], v250, s[14:15] nt
	global_load_dwordx4 v[206:209], v250, s[14:15] offset:256 nt
	s_add_u32 s14, s10, 0x30000
	s_addc_u32 s15, s11, 0
	global_load_dwordx4 v[210:213], v250, s[14:15] nt
	global_load_dwordx4 v[214:217], v250, s[14:15] offset:256 nt
	s_add_u32 s14, s10, 0x80000
	s_addc_u32 s15, s11, 0
	global_load_dwordx4 v[218:221], v250, s[14:15] nt
	global_load_dwordx4 v[222:225], v250, s[14:15] offset:256 nt
	s_add_u32 s14, s10, 0x90000
	s_addc_u32 s15, s11, 0
	global_load_dwordx4 v[226:229], v250, s[14:15] nt
	global_load_dwordx4 v[230:233], v250, s[14:15] offset:256 nt
	s_add_u32 s14, s10, 0xa0000
	s_addc_u32 s15, s11, 0
	global_load_dwordx4 v[234:237], v250, s[14:15] nt
	global_load_dwordx4 v[238:241], v250, s[14:15] offset:256 nt
	s_add_u32 s14, s10, 0xb0000
	s_addc_u32 s15, s11, 0
	global_load_dwordx4 v[242:245], v250, s[14:15] nt
	global_load_dwordx4 v[246:249], v250, s[14:15] offset:256 nt
	s_nop 0
	s_nop 0
	v_mbcnt_lo_u32_b32 v129, -1, 0
	v_mbcnt_hi_u32_b32 v150, -1, v129
	v_and_b32_e32 v142, 64, v150
	v_add_u32_e32 v151, 64, v142
	v_xor_b32_e32 v129, 16, v150
	v_cmp_lt_i32_e32 vcc, v129, v151
	s_lshl_b32 s0, s2, 2
	s_add_i32 s2, s0, 0
	v_cndmask_b32_e32 v129, v150, v129, vcc
	v_lshlrev_b32_e32 v129, 2, v129
	s_waitcnt vmcnt(14)
	v_mov_b64_e32 v[134:135], v[186:187]
	v_mov_b64_e32 v[136:137], v[188:189]
	v_mov_b64_e32 v[138:139], v[190:191]
	v_mov_b64_e32 v[140:141], v[192:193]
	v_lshlrev_b32_e32 v142, 16, v134
	v_and_b32_e32 v143, 0xffff0000, v134
	v_lshlrev_b32_e32 v134, 16, v135
	v_and_b32_e32 v135, 0xffff0000, v135
	v_lshlrev_b32_e32 v146, 16, v138
	v_and_b32_e32 v147, 0xffff0000, v138
	v_lshlrev_b32_e32 v138, 16, v139
	v_and_b32_e32 v139, 0xffff0000, v139
	v_lshlrev_b32_e32 v144, 16, v136
	v_and_b32_e32 v145, 0xffff0000, v136
	v_lshlrev_b32_e32 v148, 16, v140
	v_and_b32_e32 v149, 0xffff0000, v140
	v_pk_add_f32 v[126:127], v[126:127], v[134:135]
	v_pk_add_f32 v[124:125], v[124:125], v[142:143]
	v_pk_add_f32 v[118:119], v[118:119], v[138:139]
	v_pk_add_f32 v[116:117], v[116:117], v[146:147]
	v_lshlrev_b32_e32 v136, 16, v137
	v_and_b32_e32 v137, 0xffff0000, v137
	v_lshlrev_b32_e32 v140, 16, v141
	v_and_b32_e32 v141, 0xffff0000, v141
	v_pk_add_f32 v[120:121], v[120:121], v[144:145]
	v_pk_add_f32 v[112:113], v[112:113], v[148:149]
	v_mul_f32_e32 v134, v125, v125
	v_mul_f32_e32 v135, v127, v127
	v_mul_f32_e32 v138, v117, v117
	v_mul_f32_e32 v139, v119, v119
	v_pk_add_f32 v[122:123], v[122:123], v[136:137]
	v_pk_add_f32 v[114:115], v[114:115], v[140:141]
	v_mul_f32_e32 v136, v121, v121
	v_mul_f32_e32 v140, v113, v113
	v_fmac_f32_e32 v134, v124, v124
	v_fmac_f32_e32 v135, v126, v126
	v_fmac_f32_e32 v138, v116, v116
	v_fmac_f32_e32 v139, v118, v118
	v_mul_f32_e32 v137, v123, v123
	v_mul_f32_e32 v141, v115, v115
	v_fmac_f32_e32 v136, v120, v120
	v_fmac_f32_e32 v140, v112, v112
	v_add_f32_e32 v134, v134, v135
	v_add_f32_e32 v135, v138, v139
	v_fmac_f32_e32 v137, v122, v122
	v_fmac_f32_e32 v141, v114, v114
	v_add_f32_e32 v134, v136, v134
	v_add_f32_e32 v135, v140, v135
	v_add_f32_e32 v134, v137, v134
	v_add_f32_e32 v135, v141, v135
	v_add_f32_e32 v134, v134, v135
	ds_bpermute_b32 v135, v129, v134
	v_xor_b32_e32 v136, 32, v150
	v_cmp_lt_i32_e32 vcc, v136, v151
	s_waitcnt lgkmcnt(0)
	v_add_f32_e32 v134, v134, v135
	v_cndmask_b32_e32 v136, v150, v136, vcc
	v_lshlrev_b32_e32 v164, 2, v136
	ds_bpermute_b32 v135, v164, v134
	v_cmp_gt_u32_e32 vcc, 16, v128
	s_and_saveexec_b64 s[0:1], vcc
	s_cbranch_execz .LBB0_858
	v_lshl_add_u32 v136, v172, 4, s2
	s_waitcnt lgkmcnt(0)
	v_add_f32_e32 v134, v134, v135
	ds_write_b32 v136, v134
.LBB0_858:
	s_or_b64 exec, exec, s[0:1]
	v_or_b32_e32 v136, 16, v172
	v_add_u32_e32 v134, s3, v136
	s_waitcnt lgkmcnt(0)
	v_ashrrev_i32_e32 v135, 31, v134
	v_lshlrev_b64 v[138:139], 12, v[134:135]
	v_lshl_add_u64 v[138:139], s[10:11], 0, v[138:139]
	v_lshl_add_u64 v[142:143], v[130:131], 1, v[138:139]
	s_nop 0
	s_nop 0
	s_nop 0
	s_waitcnt vmcnt(13)
	v_mov_b64_e32 v[138:139], v[194:195]
	v_mov_b64_e32 v[140:141], v[196:197]
	v_lshlrev_b32_e32 v146, 16, v138
	v_and_b32_e32 v147, 0xffff0000, v138
	v_lshlrev_b32_e32 v138, 16, v139
	v_and_b32_e32 v139, 0xffff0000, v139
	s_waitcnt vmcnt(12)
	v_mov_b64_e32 v[142:143], v[198:199]
	v_mov_b64_e32 v[144:145], v[200:201]
	v_lshlrev_b32_e32 v150, 16, v142
	v_and_b32_e32 v151, 0xffff0000, v142
	v_lshlrev_b32_e32 v142, 16, v143
	v_and_b32_e32 v143, 0xffff0000, v143
	v_lshlrev_b32_e32 v148, 16, v140
	v_and_b32_e32 v149, 0xffff0000, v140
	v_lshlrev_b32_e32 v140, 16, v141
	v_and_b32_e32 v141, 0xffff0000, v141
	v_lshlrev_b32_e32 v152, 16, v144
	v_and_b32_e32 v153, 0xffff0000, v144
	v_pk_add_f32 v[110:111], v[110:111], v[138:139]
	v_pk_add_f32 v[108:109], v[108:109], v[146:147]
	v_pk_add_f32 v[102:103], v[102:103], v[142:143]
	v_pk_add_f32 v[100:101], v[100:101], v[150:151]
	v_lshlrev_b32_e32 v144, 16, v145
	v_and_b32_e32 v145, 0xffff0000, v145
	v_pk_add_f32 v[106:107], v[106:107], v[140:141]
	v_pk_add_f32 v[104:105], v[104:105], v[148:149]
	v_pk_add_f32 v[96:97], v[96:97], v[152:153]
	v_mul_f32_e32 v137, v109, v109
	v_mul_f32_e32 v138, v111, v111
	v_mul_f32_e32 v141, v101, v101
	v_mul_f32_e32 v142, v103, v103
	v_pk_add_f32 v[98:99], v[98:99], v[144:145]
	v_mul_f32_e32 v139, v105, v105
	v_mul_f32_e32 v143, v97, v97
	v_fmac_f32_e32 v137, v108, v108
	v_fmac_f32_e32 v138, v110, v110
	v_fmac_f32_e32 v141, v100, v100
	v_fmac_f32_e32 v142, v102, v102
	v_mul_f32_e32 v140, v107, v107
	v_mul_f32_e32 v144, v99, v99
	v_fmac_f32_e32 v139, v104, v104
	v_fmac_f32_e32 v143, v96, v96
	v_add_f32_e32 v137, v137, v138
	v_add_f32_e32 v138, v141, v142
	v_fmac_f32_e32 v140, v106, v106
	v_fmac_f32_e32 v144, v98, v98
	v_add_f32_e32 v137, v139, v137
	v_add_f32_e32 v138, v143, v138
	v_add_f32_e32 v137, v140, v137
	v_add_f32_e32 v138, v144, v138
	v_add_f32_e32 v137, v137, v138
	ds_bpermute_b32 v138, v129, v137
	s_waitcnt lgkmcnt(0)
	v_add_f32_e32 v137, v137, v138
	ds_bpermute_b32 v138, v164, v137
	s_and_saveexec_b64 s[0:1], vcc
	s_cbranch_execz .LBB0_860
	v_lshl_add_u32 v136, v136, 4, s2
	s_waitcnt lgkmcnt(0)
	v_add_f32_e32 v137, v137, v138
	ds_write_b32 v136, v137
.LBB0_860:
	s_or_b64 exec, exec, s[0:1]
	s_waitcnt lgkmcnt(0)
	v_or_b32_e32 v138, 32, v172
	v_add_u32_e32 v136, s3, v138
	v_ashrrev_i32_e32 v137, 31, v136
	v_lshlrev_b64 v[140:141], 12, v[136:137]
	v_lshl_add_u64 v[140:141], s[10:11], 0, v[140:141]
	v_lshl_add_u64 v[144:145], v[130:131], 1, v[140:141]
	s_nop 0
	s_nop 0
	s_nop 0
	s_waitcnt vmcnt(11)
	v_mov_b64_e32 v[140:141], v[202:203]
	v_mov_b64_e32 v[142:143], v[204:205]
	v_lshlrev_b32_e32 v148, 16, v140
	v_and_b32_e32 v149, 0xffff0000, v140
	v_lshlrev_b32_e32 v140, 16, v141
	v_and_b32_e32 v141, 0xffff0000, v141
	s_waitcnt vmcnt(10)
	v_mov_b64_e32 v[144:145], v[206:207]
	v_mov_b64_e32 v[146:147], v[208:209]
	v_lshlrev_b32_e32 v152, 16, v144
	v_and_b32_e32 v153, 0xffff0000, v144
	v_lshlrev_b32_e32 v144, 16, v145
	v_and_b32_e32 v145, 0xffff0000, v145
	v_lshlrev_b32_e32 v150, 16, v142
	v_and_b32_e32 v151, 0xffff0000, v142
	v_lshlrev_b32_e32 v142, 16, v143
	v_and_b32_e32 v143, 0xffff0000, v143
	v_lshlrev_b32_e32 v154, 16, v146
	v_and_b32_e32 v155, 0xffff0000, v146
	v_pk_add_f32 v[94:95], v[94:95], v[140:141]
	v_pk_add_f32 v[92:93], v[92:93], v[148:149]
	v_pk_add_f32 v[86:87], v[86:87], v[144:145]
	v_pk_add_f32 v[84:85], v[84:85], v[152:153]
	v_lshlrev_b32_e32 v146, 16, v147
	v_and_b32_e32 v147, 0xffff0000, v147
	v_pk_add_f32 v[90:91], v[90:91], v[142:143]
	v_pk_add_f32 v[88:89], v[88:89], v[150:151]
	v_pk_add_f32 v[80:81], v[80:81], v[154:155]
	v_mul_f32_e32 v139, v93, v93
	v_mul_f32_e32 v140, v95, v95
	v_mul_f32_e32 v143, v85, v85
	v_mul_f32_e32 v144, v87, v87
	v_pk_add_f32 v[82:83], v[82:83], v[146:147]
	v_mul_f32_e32 v141, v89, v89
	v_mul_f32_e32 v145, v81, v81
	v_fmac_f32_e32 v139, v92, v92
	v_fmac_f32_e32 v140, v94, v94
	v_fmac_f32_e32 v143, v84, v84
	v_fmac_f32_e32 v144, v86, v86
	v_mul_f32_e32 v142, v91, v91
	v_mul_f32_e32 v146, v83, v83
	v_fmac_f32_e32 v141, v88, v88
	v_fmac_f32_e32 v145, v80, v80
	v_add_f32_e32 v139, v139, v140
	v_add_f32_e32 v140, v143, v144
	v_fmac_f32_e32 v142, v90, v90
	v_fmac_f32_e32 v146, v82, v82
	v_add_f32_e32 v139, v141, v139
	v_add_f32_e32 v140, v145, v140
	v_add_f32_e32 v139, v142, v139
	v_add_f32_e32 v140, v146, v140
	v_add_f32_e32 v139, v139, v140
	ds_bpermute_b32 v140, v129, v139
	s_waitcnt lgkmcnt(0)
	v_add_f32_e32 v139, v139, v140
	ds_bpermute_b32 v140, v164, v139
	s_and_saveexec_b64 s[0:1], vcc
	s_cbranch_execz .LBB0_862
	v_lshl_add_u32 v138, v138, 4, s2
	s_waitcnt lgkmcnt(0)
	v_add_f32_e32 v139, v139, v140
	ds_write_b32 v138, v139
.LBB0_862:
	s_or_b64 exec, exec, s[0:1]
	s_waitcnt lgkmcnt(0)
	v_or_b32_e32 v140, 48, v172
	v_add_u32_e32 v138, s3, v140
	v_ashrrev_i32_e32 v139, 31, v138
	v_lshlrev_b64 v[142:143], 12, v[138:139]
	v_lshl_add_u64 v[142:143], s[10:11], 0, v[142:143]
	v_lshl_add_u64 v[146:147], v[130:131], 1, v[142:143]
	s_nop 0
	s_nop 0
	s_nop 0
	s_waitcnt vmcnt(9)
	v_mov_b64_e32 v[142:143], v[210:211]
	v_mov_b64_e32 v[144:145], v[212:213]
	v_lshlrev_b32_e32 v150, 16, v142
	v_and_b32_e32 v151, 0xffff0000, v142
	v_lshlrev_b32_e32 v142, 16, v143
	v_and_b32_e32 v143, 0xffff0000, v143
	s_waitcnt vmcnt(8)
	v_mov_b64_e32 v[146:147], v[214:215]
	v_mov_b64_e32 v[148:149], v[216:217]
	v_lshlrev_b32_e32 v154, 16, v146
	v_and_b32_e32 v155, 0xffff0000, v146
	v_lshlrev_b32_e32 v146, 16, v147
	v_and_b32_e32 v147, 0xffff0000, v147
	v_lshlrev_b32_e32 v152, 16, v144
	v_and_b32_e32 v153, 0xffff0000, v144
	v_lshlrev_b32_e32 v144, 16, v145
	v_and_b32_e32 v145, 0xffff0000, v145
	v_lshlrev_b32_e32 v156, 16, v148
	v_and_b32_e32 v157, 0xffff0000, v148
	v_pk_add_f32 v[78:79], v[78:79], v[142:143]
	v_pk_add_f32 v[76:77], v[76:77], v[150:151]
	v_pk_add_f32 v[70:71], v[70:71], v[146:147]
	v_pk_add_f32 v[68:69], v[68:69], v[154:155]
	v_lshlrev_b32_e32 v148, 16, v149
	v_and_b32_e32 v149, 0xffff0000, v149
	v_pk_add_f32 v[74:75], v[74:75], v[144:145]
	v_pk_add_f32 v[72:73], v[72:73], v[152:153]
	v_pk_add_f32 v[64:65], v[64:65], v[156:157]
	v_mul_f32_e32 v141, v77, v77
	v_mul_f32_e32 v142, v79, v79
	v_mul_f32_e32 v145, v69, v69
	v_mul_f32_e32 v146, v71, v71
	v_pk_add_f32 v[66:67], v[66:67], v[148:149]
	v_mul_f32_e32 v143, v73, v73
	v_mul_f32_e32 v147, v65, v65
	v_fmac_f32_e32 v141, v76, v76
	v_fmac_f32_e32 v142, v78, v78
	v_fmac_f32_e32 v145, v68, v68
	v_fmac_f32_e32 v146, v70, v70
	v_mul_f32_e32 v144, v75, v75
	v_mul_f32_e32 v148, v67, v67
	v_fmac_f32_e32 v143, v72, v72
	v_fmac_f32_e32 v147, v64, v64
	v_add_f32_e32 v141, v141, v142
	v_add_f32_e32 v142, v145, v146
	v_fmac_f32_e32 v144, v74, v74
	v_fmac_f32_e32 v148, v66, v66
	v_add_f32_e32 v141, v143, v141
	v_add_f32_e32 v142, v147, v142
	v_add_f32_e32 v141, v144, v141
	v_add_f32_e32 v142, v148, v142
	v_add_f32_e32 v141, v141, v142
	ds_bpermute_b32 v142, v129, v141
	s_waitcnt lgkmcnt(0)
	v_add_f32_e32 v141, v141, v142
	ds_bpermute_b32 v142, v164, v141
	s_and_saveexec_b64 s[0:1], vcc
	s_cbranch_execz .LBB0_864
	v_lshl_add_u32 v140, v140, 4, s2
	s_waitcnt lgkmcnt(0)
	v_add_f32_e32 v141, v141, v142
	ds_write_b32 v140, v141
.LBB0_864:
	s_or_b64 exec, exec, s[0:1]
	v_add_u32_e32 v140, 0x80, v172
	v_add_u32_e32 v156, s3, v140
	v_ashrrev_i32_e32 v157, 31, v156
	s_waitcnt lgkmcnt(0)
	v_lshlrev_b64 v[142:143], 12, v[156:157]
	v_lshl_add_u64 v[142:143], s[10:11], 0, v[142:143]
	v_lshl_add_u64 v[146:147], v[130:131], 1, v[142:143]
	s_nop 0
	s_nop 0
	s_nop 0
	s_waitcnt vmcnt(7)
	v_mov_b64_e32 v[142:143], v[218:219]
	v_mov_b64_e32 v[144:145], v[220:221]
	v_lshlrev_b32_e32 v150, 16, v142
	v_and_b32_e32 v151, 0xffff0000, v142
	v_lshlrev_b32_e32 v142, 16, v143
	v_and_b32_e32 v143, 0xffff0000, v143
	s_waitcnt vmcnt(6)
	v_mov_b64_e32 v[146:147], v[222:223]
	v_mov_b64_e32 v[148:149], v[224:225]
	v_lshlrev_b32_e32 v154, 16, v146
	v_and_b32_e32 v155, 0xffff0000, v146
	v_lshlrev_b32_e32 v146, 16, v147
	v_and_b32_e32 v147, 0xffff0000, v147
	v_lshlrev_b32_e32 v152, 16, v144
	v_and_b32_e32 v153, 0xffff0000, v144
	v_lshlrev_b32_e32 v144, 16, v145
	v_and_b32_e32 v145, 0xffff0000, v145
	v_lshlrev_b32_e32 v158, 16, v148
	v_and_b32_e32 v159, 0xffff0000, v148
	v_pk_add_f32 v[62:63], v[62:63], v[142:143]
	v_pk_add_f32 v[60:61], v[60:61], v[150:151]
	v_pk_add_f32 v[54:55], v[54:55], v[146:147]
	v_pk_add_f32 v[52:53], v[52:53], v[154:155]
	v_lshlrev_b32_e32 v148, 16, v149
	v_and_b32_e32 v149, 0xffff0000, v149
	v_pk_add_f32 v[58:59], v[58:59], v[144:145]
	v_pk_add_f32 v[56:57], v[56:57], v[152:153]
	v_pk_add_f32 v[48:49], v[48:49], v[158:159]
	v_mul_f32_e32 v141, v61, v61
	v_mul_f32_e32 v142, v63, v63
	v_mul_f32_e32 v145, v53, v53
	v_mul_f32_e32 v146, v55, v55
	v_pk_add_f32 v[50:51], v[50:51], v[148:149]
	v_mul_f32_e32 v143, v57, v57
	v_mul_f32_e32 v147, v49, v49
	v_fmac_f32_e32 v141, v60, v60
	v_fmac_f32_e32 v142, v62, v62
	v_fmac_f32_e32 v145, v52, v52
	v_fmac_f32_e32 v146, v54, v54
	v_mul_f32_e32 v144, v59, v59
	v_mul_f32_e32 v148, v51, v51
	v_fmac_f32_e32 v143, v56, v56
	v_fmac_f32_e32 v147, v48, v48
	v_add_f32_e32 v141, v141, v142
	v_add_f32_e32 v142, v145, v146
	v_fmac_f32_e32 v144, v58, v58
	v_fmac_f32_e32 v148, v50, v50
	v_add_f32_e32 v141, v143, v141
	v_add_f32_e32 v142, v147, v142
	v_add_f32_e32 v141, v144, v141
	v_add_f32_e32 v142, v148, v142
	v_add_f32_e32 v141, v141, v142
	ds_bpermute_b32 v142, v129, v141
	s_waitcnt lgkmcnt(0)
	v_add_f32_e32 v141, v141, v142
	ds_bpermute_b32 v142, v164, v141
	s_and_saveexec_b64 s[0:1], vcc
	s_cbranch_execz .LBB0_866
	v_lshl_add_u32 v140, v140, 4, s2
	s_waitcnt lgkmcnt(0)
	v_add_f32_e32 v141, v141, v142
	ds_write_b32 v140, v141
.LBB0_866:
	s_or_b64 exec, exec, s[0:1]
	v_add_u32_e32 v140, 0x90, v172
	v_add_u32_e32 v158, s3, v140
	v_ashrrev_i32_e32 v159, 31, v158
	s_waitcnt lgkmcnt(0)
	v_lshlrev_b64 v[142:143], 12, v[158:159]
	v_lshl_add_u64 v[142:143], s[10:11], 0, v[142:143]
	v_lshl_add_u64 v[146:147], v[130:131], 1, v[142:143]
	s_nop 0
	s_nop 0
	s_nop 0
	s_waitcnt vmcnt(5)
	v_mov_b64_e32 v[142:143], v[226:227]
	v_mov_b64_e32 v[144:145], v[228:229]
	v_lshlrev_b32_e32 v150, 16, v142
	v_and_b32_e32 v151, 0xffff0000, v142
	v_lshlrev_b32_e32 v142, 16, v143
	v_and_b32_e32 v143, 0xffff0000, v143
	s_waitcnt vmcnt(4)
	v_mov_b64_e32 v[146:147], v[230:231]
	v_mov_b64_e32 v[148:149], v[232:233]
	v_lshlrev_b32_e32 v154, 16, v146
	v_and_b32_e32 v155, 0xffff0000, v146
	v_lshlrev_b32_e32 v146, 16, v147
	v_and_b32_e32 v147, 0xffff0000, v147
	v_lshlrev_b32_e32 v152, 16, v144
	v_and_b32_e32 v153, 0xffff0000, v144
	v_lshlrev_b32_e32 v144, 16, v145
	v_and_b32_e32 v145, 0xffff0000, v145
	v_lshlrev_b32_e32 v160, 16, v148
	v_and_b32_e32 v161, 0xffff0000, v148
	v_pk_add_f32 v[46:47], v[46:47], v[142:143]
	v_pk_add_f32 v[44:45], v[44:45], v[150:151]
	v_pk_add_f32 v[38:39], v[38:39], v[146:147]
	v_pk_add_f32 v[36:37], v[36:37], v[154:155]
	v_lshlrev_b32_e32 v148, 16, v149
	v_and_b32_e32 v149, 0xffff0000, v149
	v_pk_add_f32 v[42:43], v[42:43], v[144:145]
	v_pk_add_f32 v[40:41], v[40:41], v[152:153]
	v_pk_add_f32 v[32:33], v[32:33], v[160:161]
	v_mul_f32_e32 v141, v45, v45
	v_mul_f32_e32 v142, v47, v47
	v_mul_f32_e32 v145, v37, v37
	v_mul_f32_e32 v146, v39, v39
	v_pk_add_f32 v[34:35], v[34:35], v[148:149]
	v_mul_f32_e32 v143, v41, v41
	v_mul_f32_e32 v147, v33, v33
	v_fmac_f32_e32 v141, v44, v44
	v_fmac_f32_e32 v142, v46, v46
	v_fmac_f32_e32 v145, v36, v36
	v_fmac_f32_e32 v146, v38, v38
	v_mul_f32_e32 v144, v43, v43
	v_mul_f32_e32 v148, v35, v35
	v_fmac_f32_e32 v143, v40, v40
	v_fmac_f32_e32 v147, v32, v32
	v_add_f32_e32 v141, v141, v142
	v_add_f32_e32 v142, v145, v146
	v_fmac_f32_e32 v144, v42, v42
	v_fmac_f32_e32 v148, v34, v34
	v_add_f32_e32 v141, v143, v141
	v_add_f32_e32 v142, v147, v142
	v_add_f32_e32 v141, v144, v141
	v_add_f32_e32 v142, v148, v142
	v_add_f32_e32 v141, v141, v142
	ds_bpermute_b32 v142, v129, v141
	s_waitcnt lgkmcnt(0)
	v_add_f32_e32 v141, v141, v142
	ds_bpermute_b32 v142, v164, v141
	s_and_saveexec_b64 s[0:1], vcc
	s_cbranch_execz .LBB0_868
	v_lshl_add_u32 v140, v140, 4, s2
	s_waitcnt lgkmcnt(0)
	v_add_f32_e32 v141, v141, v142
	ds_write_b32 v140, v141
.LBB0_868:
	s_or_b64 exec, exec, s[0:1]
	v_add_u32_e32 v140, 0xa0, v172
	v_add_u32_e32 v160, s3, v140
	v_ashrrev_i32_e32 v161, 31, v160
	s_waitcnt lgkmcnt(0)
	v_lshlrev_b64 v[142:143], 12, v[160:161]
	v_lshl_add_u64 v[142:143], s[10:11], 0, v[142:143]
	v_lshl_add_u64 v[146:147], v[130:131], 1, v[142:143]
	s_nop 0
	s_nop 0
	s_nop 0
	s_waitcnt vmcnt(3)
	v_mov_b64_e32 v[142:143], v[234:235]
	v_mov_b64_e32 v[144:145], v[236:237]
	v_lshlrev_b32_e32 v150, 16, v142
	v_and_b32_e32 v151, 0xffff0000, v142
	v_lshlrev_b32_e32 v142, 16, v143
	v_and_b32_e32 v143, 0xffff0000, v143
	s_waitcnt vmcnt(2)
	v_mov_b64_e32 v[146:147], v[238:239]
	v_mov_b64_e32 v[148:149], v[240:241]
	v_lshlrev_b32_e32 v154, 16, v146
	v_and_b32_e32 v155, 0xffff0000, v146
	v_lshlrev_b32_e32 v146, 16, v147
	v_and_b32_e32 v147, 0xffff0000, v147
	v_lshlrev_b32_e32 v152, 16, v144
	v_and_b32_e32 v153, 0xffff0000, v144
	v_lshlrev_b32_e32 v144, 16, v145
	v_and_b32_e32 v145, 0xffff0000, v145
	v_lshlrev_b32_e32 v162, 16, v148
	v_and_b32_e32 v163, 0xffff0000, v148
	v_pk_add_f32 v[30:31], v[30:31], v[142:143]
	v_pk_add_f32 v[28:29], v[28:29], v[150:151]
	v_pk_add_f32 v[22:23], v[22:23], v[146:147]
	v_pk_add_f32 v[20:21], v[20:21], v[154:155]
	v_lshlrev_b32_e32 v148, 16, v149
	v_and_b32_e32 v149, 0xffff0000, v149
	v_pk_add_f32 v[26:27], v[26:27], v[144:145]
	v_pk_add_f32 v[24:25], v[24:25], v[152:153]
	v_pk_add_f32 v[16:17], v[16:17], v[162:163]
	v_mul_f32_e32 v141, v29, v29
	v_mul_f32_e32 v142, v31, v31
	v_mul_f32_e32 v145, v21, v21
	v_mul_f32_e32 v146, v23, v23
	v_pk_add_f32 v[18:19], v[18:19], v[148:149]
	v_mul_f32_e32 v143, v25, v25
	v_mul_f32_e32 v147, v17, v17
	v_fmac_f32_e32 v141, v28, v28
	v_fmac_f32_e32 v142, v30, v30
	v_fmac_f32_e32 v145, v20, v20
	v_fmac_f32_e32 v146, v22, v22
	v_mul_f32_e32 v144, v27, v27
	v_mul_f32_e32 v148, v19, v19
	v_fmac_f32_e32 v143, v24, v24
	v_fmac_f32_e32 v147, v16, v16
	v_add_f32_e32 v141, v141, v142
	v_add_f32_e32 v142, v145, v146
	v_fmac_f32_e32 v144, v26, v26
	v_fmac_f32_e32 v148, v18, v18
	v_add_f32_e32 v141, v143, v141
	v_add_f32_e32 v142, v147, v142
	v_add_f32_e32 v141, v144, v141
	v_add_f32_e32 v142, v148, v142
	v_add_f32_e32 v141, v141, v142
	ds_bpermute_b32 v142, v129, v141
	s_waitcnt lgkmcnt(0)
	v_add_f32_e32 v141, v141, v142
	ds_bpermute_b32 v142, v164, v141
	s_and_saveexec_b64 s[0:1], vcc
	s_cbranch_execz .LBB0_870
	v_lshl_add_u32 v140, v140, 4, s2
	s_waitcnt lgkmcnt(0)
	v_add_f32_e32 v141, v141, v142
	ds_write_b32 v140, v141
.LBB0_870:
	s_or_b64 exec, exec, s[0:1]
	v_add_u32_e32 v165, 0xb0, v172
	v_add_u32_e32 v162, s3, v165
	v_ashrrev_i32_e32 v163, 31, v162
	v_lshlrev_b64 v[140:141], 12, v[162:163]
	v_lshl_add_u64 v[140:141], s[10:11], 0, v[140:141]
	v_lshl_add_u64 v[144:145], v[130:131], 1, v[140:141]
	s_waitcnt lgkmcnt(0)
	s_nop 0
	s_nop 0
	s_nop 0
	s_waitcnt vmcnt(1)
	v_mov_b64_e32 v[140:141], v[242:243]
	v_mov_b64_e32 v[142:143], v[244:245]
	v_lshlrev_b32_e32 v148, 16, v140
	v_and_b32_e32 v149, 0xffff0000, v140
	v_lshlrev_b32_e32 v140, 16, v141
	v_and_b32_e32 v141, 0xffff0000, v141
	v_lshlrev_b32_e32 v150, 16, v142
	v_and_b32_e32 v151, 0xffff0000, v142
	v_lshlrev_b32_e32 v142, 16, v143
	v_and_b32_e32 v143, 0xffff0000, v143
	s_waitcnt vmcnt(0)
	v_mov_b64_e32 v[144:145], v[246:247]
	v_mov_b64_e32 v[146:147], v[248:249]
	v_lshlrev_b32_e32 v166, 16, v144
	v_and_b32_e32 v167, 0xffff0000, v144
	v_lshlrev_b32_e32 v144, 16, v145
	v_and_b32_e32 v145, 0xffff0000, v145
	v_lshlrev_b32_e32 v168, 16, v146
	v_and_b32_e32 v169, 0xffff0000, v146
	v_lshlrev_b32_e32 v170, 16, v147
	v_and_b32_e32 v171, 0xffff0000, v147
	v_pk_add_f32 v[152:153], v[14:15], v[140:141]
	v_pk_add_f32 v[154:155], v[12:13], v[148:149]
	v_pk_add_f32 v[146:147], v[10:11], v[142:143]
	v_pk_add_f32 v[142:143], v[6:7], v[144:145]
	v_pk_add_f32 v[148:149], v[4:5], v[166:167]
	v_pk_add_f32 v[150:151], v[8:9], v[150:151]
	v_pk_add_f32 v[144:145], v[0:1], v[168:169]
	v_mul_f32_e32 v0, v155, v155
	v_mul_f32_e32 v1, v153, v153
	v_mul_f32_e32 v4, v149, v149
	v_mul_f32_e32 v5, v143, v143
	v_pk_add_f32 v[140:141], v[2:3], v[170:171]
	v_mul_f32_e32 v2, v151, v151
	v_mul_f32_e32 v6, v145, v145
	v_fmac_f32_e32 v0, v154, v154
	v_fmac_f32_e32 v1, v152, v152
	v_fmac_f32_e32 v4, v148, v148
	v_fmac_f32_e32 v5, v142, v142
	v_mul_f32_e32 v3, v147, v147
	v_mul_f32_e32 v7, v141, v141
	v_fmac_f32_e32 v2, v150, v150
	v_fmac_f32_e32 v6, v144, v144
	v_add_f32_e32 v0, v0, v1
	v_add_f32_e32 v1, v4, v5
	v_fmac_f32_e32 v3, v146, v146
	v_fmac_f32_e32 v7, v140, v140
	v_add_f32_e32 v0, v2, v0
	v_add_f32_e32 v1, v6, v1
	v_add_f32_e32 v0, v3, v0
	v_add_f32_e32 v1, v7, v1
	v_add_f32_e32 v0, v0, v1
	ds_bpermute_b32 v1, v129, v0
	s_waitcnt lgkmcnt(0)
	v_add_f32_e32 v0, v0, v1
	ds_bpermute_b32 v1, v164, v0
	s_and_saveexec_b64 s[0:1], vcc
	s_cbranch_execz .LBB0_872
	v_lshl_add_u32 v2, v165, 4, s2
	s_waitcnt lgkmcnt(0)
	v_add_f32_e32 v0, v0, v1
	ds_write_b32 v2, v0
